# attention tile loop rewritten as intra-wave software pipeline (QK of next tile and PV of previous tile issued under the softmax VALU; third V buffer in LDS)
# speedup vs baseline: 1.1516x; 1.0075x over previous
.LBB0_1098:
	s_xor_b64 s[30:31], s[0:1], -1
	s_and_b64 s[0:1], s[0:1], exec
	s_cselect_b32 s1, s19, s37
	v_mov_b32_e32 v174, v190
	s_lshl_b32 s14, s1, 15
	s_lshl_b32 s0, s1, 16
	s_add_u32 s4, s16, s0
	v_readfirstlane_b32 s7, v174
	s_addc_u32 s5, s17, 0
	s_ashr_i32 s0, s7, 6
	v_lshlrev_b32_e32 v1, 3, v174
	s_lshl_b32 s6, s1, 8
	s_lshl_b32 s38, s1, 2
	s_ashr_i32 s1, s0, 31
	v_ashrrev_i32_e32 v0, 4, v174
	v_and_b32_e32 v2, 0x78, v1
	v_and_b32_e32 v175, 31, v174
	v_bfe_u32 v176, v174, 5, 1
	s_lshl_b32 s39, s0, 5
	s_and_b32 s7, s7, 0x3fffffc0
	s_lshl_b64 s[28:29], s[0:1], 13
	v_lshlrev_b32_e32 v2, 1, v2
	v_lshlrev_b32_e32 v3, 8, v0
	v_lshlrev_b32_e32 v10, 8, v175
	v_lshlrev_b32_e32 v11, 4, v176
	s_add_u32 s0, s4, s28
	v_or_b32_e32 v148, v2, v3
	v_or_b32_e32 v12, v11, v10
	s_addc_u32 s1, s5, s29
	global_load_dwordx4 v[96:99], v148, s[22:23]
	global_load_dwordx4 v[100:103], v148, s[20:21]
	global_load_dwordx4 v[136:139], v148, s[42:43]
	global_load_dwordx4 v[140:143], v148, s[26:27]
	global_load_dwordx4 v[104:107], v12, s[0:1]
	global_load_dwordx4 v[108:111], v12, s[0:1] offset:32
	global_load_dwordx4 v[112:115], v12, s[0:1] offset:64
	global_load_dwordx4 v[116:119], v12, s[0:1] offset:96
	global_load_dwordx4 v[120:123], v12, s[0:1] offset:128
	global_load_dwordx4 v[124:127], v12, s[0:1] offset:160
	global_load_dwordx4 v[128:131], v12, s[0:1] offset:192
	global_load_dwordx4 v[132:135], v12, s[0:1] offset:224
	v_and_b32_e32 v6, 0xfffff0, v0
	v_lshlrev_b32_e32 v7, 1, v0
	v_and_or_b32 v6, v7, 8, v6
	v_lshrrev_b32_e32 v7, 1, v0
	v_and_b32_e32 v8, 3, v0
	v_add_u32_e32 v0, 32, v0
	v_and_b32_e32 v4, 63, v174
	v_and_b32_e32 v9, 0xfffff0, v0
	v_lshlrev_b32_e32 v0, 1, v0
	v_lshlrev_b32_e32 v12, 4, v174
	s_lshl_b32 s0, s7, 2
	v_and_or_b32 v0, v0, 8, v9
	v_lshlrev_b32_e32 v9, 3, v4
	v_and_b32_e32 v13, 0xc0, v12
	v_lshlrev_b32_e32 v14, 1, v174
	s_add_i32 s0, s0, 0
	v_lshlrev_b32_e32 v5, 2, v176
	v_and_or_b32 v13, v9, 24, v13
	v_and_b32_e32 v14, 32, v14
	v_and_b32_e32 v9, 0x100, v9
	s_add_i32 s18, s38, 4
	s_add_i32 s39, s39, s6
	s_add_i32 s4, s0, 0x10000
	v_lshrrev_b32_e32 v6, 1, v6
	v_bfe_u32 v1, v1, 5, 2
	v_lshrrev_b32_e32 v0, 1, v0
	v_or3_b32 v9, v13, v14, v9
	v_subrev_u32_e32 v13, s6, v5
	s_cmp_lg_u32 0, -1
	v_or_b32_e32 v6, v6, v1
	v_and_or_b32 v7, v7, 4, v8
	v_or_b32_e32 v0, v0, v1
	v_and_b32_e32 v1, 0x70, v174
	v_cvt_f32_i32_e32 v13, v13
	s_cselect_b32 s0, 0, 0
	v_lshlrev_b32_e32 v6, 9, v6
	v_lshlrev_b32_e32 v7, 6, v7
	v_and_b32_e32 v8, 48, v2
	v_lshlrev_b32_e32 v0, 9, v0
	v_bitop3_b32 v1, v2, v3, v1 bitop3:0xde
	v_add_u32_e32 v178, s0, v9
	s_movk_i32 s0, 0x70
	v_or3_b32 v0, v0, v7, v8
	v_or3_b32 v6, v6, v7, v8
	v_add_u32_e32 v182, 0, v1
	v_and_b32_e32 v1, 0x70, v12
	v_bitop3_b32 v2, v11, v12, s0 bitop3:0x78
	s_movk_i32 s0, 0x60
	s_waitcnt vmcnt(0)
	v_add_u32_e32 v180, 0, v6
	v_add_u32_e32 v181, 0, v0
	v_add_u32_e32 v0, 0, v10
	v_bitop3_b32 v3, v11, v1, 32 bitop3:0x36
	v_bitop3_b32 v6, v11, v1, 64 bitop3:0x36
	v_bitop3_b32 v1, v11, v1, s0 bitop3:0x36
	v_cmp_gt_u32_e64 s[0:1], 32, v4
	v_or_b32_e32 v4, s39, v175
	v_mov_b32_e32 v32, v149
	v_mov_b32_e32 v33, v149
	v_mov_b32_e32 v46, v149
	v_mov_b32_e32 v47, v149
	v_mul_f32_e32 v179, v172, v13
	v_add_u32_e32 v177, s4, v11
	v_sub_u32_e32 v184, v4, v5
	v_mov_b32_e32 v34, v149
	v_mov_b32_e32 v35, v149
	v_mov_b32_e32 v36, v149
	v_mov_b32_e32 v37, v149
	v_mov_b32_e32 v38, v149
	v_mov_b32_e32 v39, v149
	v_mov_b32_e32 v40, v149
	v_mov_b32_e32 v41, v149
	v_mov_b32_e32 v42, v149
	v_mov_b32_e32 v43, v149
	v_mov_b32_e32 v44, v149
	v_mov_b32_e32 v45, v149
	v_add_u32_e32 v186, v0, v2
	v_add_u32_e32 v187, v0, v3
	v_add_u32_e32 v188, v0, v6
	v_add_u32_e32 v189, v0, v1
	v_mov_b64_e32 v[62:63], v[46:47]
	v_mov_b64_e32 v[16:17], v[32:33]
	v_mov_b64_e32 v[0:1], v[32:33]
	s_mov_b32 s12, 0
	v_lshl_add_u32 v183, v175, 2, s4
	v_mov_b32_e32 v203, 0xf149f2ca
	v_mov_b32_e32 v185, 0
	s_movk_i32 s13, 0x7f
	s_mov_b64 s[46:47], s[2:3]
	s_mov_b64 s[40:41], s[24:25]
	v_mov_b64_e32 v[60:61], v[44:45]
	v_mov_b64_e32 v[58:59], v[42:43]
	v_mov_b64_e32 v[56:57], v[40:41]
	v_mov_b64_e32 v[54:55], v[38:39]
	v_mov_b64_e32 v[52:53], v[36:37]
	v_mov_b64_e32 v[50:51], v[34:35]
	v_mov_b64_e32 v[48:49], v[32:33]
	v_mov_b64_e32 v[18:19], v[34:35]
	v_mov_b64_e32 v[20:21], v[36:37]
	v_mov_b64_e32 v[22:23], v[38:39]
	v_mov_b64_e32 v[24:25], v[40:41]
	v_mov_b64_e32 v[26:27], v[42:43]
	v_mov_b64_e32 v[28:29], v[44:45]
	v_mov_b64_e32 v[30:31], v[46:47]
	v_mov_b64_e32 v[2:3], v[34:35]
	v_mov_b64_e32 v[4:5], v[36:37]
	v_mov_b64_e32 v[6:7], v[38:39]
	v_mov_b64_e32 v[8:9], v[40:41]
	v_mov_b64_e32 v[10:11], v[42:43]
	v_mov_b64_e32 v[12:13], v[44:45]
	v_mov_b64_e32 v[14:15], v[46:47]
	s_waitcnt vmcnt(11)
	ds_write_b128 v180, v[96:99]
	s_waitcnt vmcnt(10)
	ds_write_b128 v181, v[100:103]
	s_waitcnt vmcnt(9)
	ds_write_b128 v182, v[136:139] offset:32768
	s_waitcnt vmcnt(8)
	ds_write_b128 v182, v[140:143] offset:40960
	s_waitcnt lgkmcnt(0)
	s_barrier
	v_add_u32_e32 v168, 0x4000, v148
	global_load_dwordx4 v[136:139], v168, s[42:43]
	global_load_dwordx4 v[140:143], v168, s[26:27]
	v_add_u32_e32 v169, 0x4000, v168
	s_mov_b32 s13, 0
	s_mov_b32 s12, 0
	s_mov_b32 s6, 0x11000
	s_mov_b32 s7, 0
	s_mov_b32 s8, 0x4000
	ds_read_b128 v[236:239], v186 offset:32768
	ds_read_b128 v[240:243], v186 offset:40960
	v_mov_b32_e32 v244, 0
	v_mov_b32_e32 v245, 0
	v_mov_b32_e32 v246, 0
	v_mov_b32_e32 v247, 0
	v_add_u32_e32 v200, s6, v180
	v_add_u32_e32 v201, s6, v181
	ds_write_b128 v200, v[244:247]
	ds_write_b128 v201, v[244:247]
	v_mov_b32_e32 v204, 0
	v_mov_b32_e32 v205, 0
	v_mov_b32_e32 v206, 0
	v_mov_b32_e32 v207, 0
	v_mov_b32_e32 v208, 0
	v_mov_b32_e32 v209, 0
	v_mov_b32_e32 v210, 0
	v_mov_b32_e32 v211, 0
	v_mov_b32_e32 v212, 0
	v_mov_b32_e32 v213, 0
	v_mov_b32_e32 v214, 0
	v_mov_b32_e32 v215, 0
	v_mov_b32_e32 v216, 0
	v_mov_b32_e32 v217, 0
	v_mov_b32_e32 v218, 0
	v_mov_b32_e32 v219, 0
	v_cvt_f32_u32_e32 v64, s13
	v_mov_b32_e32 v165, v164
	v_fma_f32 v64, v172, v64, v179
	v_add_f32_e32 v68, v173, v64
	v_add_f32_e32 v72, v173, v68
	v_add_f32_e32 v76, v173, v72
	v_add_f32_e32 v65, v172, v64
	v_add_f32_e32 v69, v172, v68
	v_add_f32_e32 v73, v172, v72
	v_add_f32_e32 v77, v172, v76
	v_pk_add_f32 v[66:67], v[162:163], v[64:65] op_sel_hi:[1,0]
	v_pk_add_f32 v[70:71], v[162:163], v[68:69] op_sel_hi:[1,0]
	v_pk_add_f32 v[74:75], v[162:163], v[72:73] op_sel_hi:[1,0]
	v_pk_add_f32 v[78:79], v[162:163], v[76:77] op_sel_hi:[1,0]
	v_pk_add_f32 v[82:83], v[164:165], v[66:67]
	v_pk_add_f32 v[80:81], v[166:167], v[64:65]
	v_pk_add_f32 v[86:87], v[164:165], v[70:71]
	v_pk_add_f32 v[84:85], v[164:165], v[68:69]
	v_pk_add_f32 v[90:91], v[164:165], v[74:75]
	v_pk_add_f32 v[88:89], v[164:165], v[72:73]
	v_pk_add_f32 v[94:95], v[164:165], v[78:79]
	v_pk_add_f32 v[92:93], v[164:165], v[76:77]
	s_addk_i32 s13, 0x40
	s_waitcnt lgkmcnt(3)
	v_mfma_f32_32x32x16_bf16 v[64:79], v[236:239], v[104:107], v[64:79]
	ds_read_b128 v[236:239], v187 offset:32768
	s_waitcnt lgkmcnt(3)
	v_mfma_f32_32x32x16_bf16 v[80:95], v[240:243], v[104:107], v[80:95]
	ds_read_b128 v[240:243], v187 offset:40960
	s_waitcnt lgkmcnt(1)
	v_mfma_f32_32x32x16_bf16 v[64:79], v[236:239], v[108:111], v[64:79]
	ds_read_b128 v[236:239], v188 offset:32768
	s_waitcnt lgkmcnt(1)
	v_mfma_f32_32x32x16_bf16 v[80:95], v[240:243], v[108:111], v[80:95]
	ds_read_b128 v[240:243], v188 offset:40960
	s_waitcnt lgkmcnt(1)
	v_mfma_f32_32x32x16_bf16 v[64:79], v[236:239], v[112:115], v[64:79]
	ds_read_b128 v[236:239], v189 offset:32768
	s_waitcnt lgkmcnt(1)
	v_mfma_f32_32x32x16_bf16 v[80:95], v[240:243], v[112:115], v[80:95]
	ds_read_b128 v[240:243], v189 offset:40960
	s_waitcnt lgkmcnt(1)
	v_mfma_f32_32x32x16_bf16 v[64:79], v[236:239], v[116:119], v[64:79]
	ds_read_b128 v[236:239], v186 offset:32896
	s_waitcnt lgkmcnt(1)
	v_mfma_f32_32x32x16_bf16 v[80:95], v[240:243], v[116:119], v[80:95]
	ds_read_b128 v[240:243], v186 offset:41088
	s_waitcnt lgkmcnt(1)
	v_mfma_f32_32x32x16_bf16 v[64:79], v[236:239], v[120:123], v[64:79]
	ds_read_b128 v[236:239], v187 offset:32896
	s_waitcnt lgkmcnt(1)
	v_mfma_f32_32x32x16_bf16 v[80:95], v[240:243], v[120:123], v[80:95]
	ds_read_b128 v[240:243], v187 offset:41088
	s_waitcnt lgkmcnt(1)
	v_mfma_f32_32x32x16_bf16 v[64:79], v[236:239], v[124:127], v[64:79]
	ds_read_b128 v[236:239], v188 offset:32896
	s_waitcnt lgkmcnt(1)
	v_mfma_f32_32x32x16_bf16 v[80:95], v[240:243], v[124:127], v[80:95]
	ds_read_b128 v[240:243], v188 offset:41088
	s_waitcnt lgkmcnt(1)
	v_mfma_f32_32x32x16_bf16 v[64:79], v[236:239], v[128:131], v[64:79]
	ds_read_b128 v[236:239], v189 offset:32896
	s_waitcnt lgkmcnt(1)
	v_mfma_f32_32x32x16_bf16 v[80:95], v[240:243], v[128:131], v[80:95]
	ds_read_b128 v[240:243], v189 offset:41088
	s_waitcnt lgkmcnt(1)
	v_mfma_f32_32x32x16_bf16 v[64:79], v[236:239], v[132:135], v[64:79]
	s_waitcnt lgkmcnt(0)
	v_mfma_f32_32x32x16_bf16 v[80:95], v[240:243], v[132:135], v[80:95]
	s_waitcnt vmcnt(0)
	ds_write_b128 v182, v[136:139] offset:49152
	ds_write_b128 v182, v[140:143] offset:57344
	s_waitcnt lgkmcnt(0)
	s_barrier
.Lat_loop:
	s_add_i32 s4, s12, 2
	s_cmp_lt_u32 s4, s18
	s_cselect_b64 s[34:35], -1, 0
	global_load_dwordx4 v[96:99], v168, s[22:23]
	global_load_dwordx4 v[100:103], v168, s[20:21]
	s_and_b64 vcc, exec, s[34:35]
	s_cbranch_vccz .Lat_nle
	global_load_dwordx4 v[136:139], v169, s[42:43]
	global_load_dwordx4 v[140:143], v169, s[26:27]
.Lat_nle:
	v_add_u32_e32 v168, 0x4000, v168
	v_add_u32_e32 v169, 0x4000, v169
	v_add_u32_e32 v165, s6, v178
	s_add_i32 s5, s13, -1
	s_cmp_gt_i32 s5, s39
	s_cselect_b64 s[46:47], -1, 0
	ds_read_b64_tr_b16 v[220:221], v165 offset:0
	ds_read_b64_tr_b16 v[222:223], v165 offset:2048
	ds_read_b64_tr_b16 v[224:225], v165 offset:4096
	ds_read_b64_tr_b16 v[226:227], v165 offset:6144
	ds_read_b64_tr_b16 v[228:229], v165 offset:8192
	ds_read_b64_tr_b16 v[230:231], v165 offset:10240
	ds_read_b64_tr_b16 v[232:233], v165 offset:12288
	ds_read_b64_tr_b16 v[234:235], v165 offset:14336
	s_and_b64 vcc, exec, s[46:47]
	s_cbranch_vccz .Lat_nme
	v_cmp_gt_i32_e64 s[48:49], 0, v184
	v_cmp_gt_i32_e64 s[50:51], 1, v184
	v_cmp_gt_i32_e64 s[52:53], 2, v184
	v_cmp_gt_i32_e64 s[54:55], 3, v184
	v_cmp_gt_i32_e64 s[56:57], 8, v184
	v_cmp_gt_i32_e64 s[58:59], 9, v184
	v_cmp_gt_i32_e64 s[60:61], 10, v184
	v_cmp_gt_i32_e64 s[62:63], 11, v184
	v_cndmask_b32_e64 v64, v64, v198, s[48:49]
	v_cndmask_b32_e64 v65, v65, v198, s[50:51]
	v_cndmask_b32_e64 v66, v66, v198, s[52:53]
	v_cndmask_b32_e64 v67, v67, v198, s[54:55]
	v_cndmask_b32_e64 v68, v68, v198, s[56:57]
	v_cndmask_b32_e64 v69, v69, v198, s[58:59]
	v_cndmask_b32_e64 v70, v70, v198, s[60:61]
	v_cndmask_b32_e64 v71, v71, v198, s[62:63]
	v_cmp_gt_i32_e64 s[48:49], 16, v184
	v_cmp_gt_i32_e64 s[50:51], 17, v184
	v_cmp_gt_i32_e64 s[52:53], 18, v184
	v_cmp_gt_i32_e64 s[54:55], 19, v184
	v_cmp_gt_i32_e64 s[56:57], 24, v184
	v_cmp_gt_i32_e64 s[58:59], 25, v184
	v_cmp_gt_i32_e64 s[60:61], 26, v184
	v_cmp_gt_i32_e64 s[62:63], 27, v184
	v_cndmask_b32_e64 v72, v72, v198, s[48:49]
	v_cndmask_b32_e64 v73, v73, v198, s[50:51]
	v_cndmask_b32_e64 v74, v74, v198, s[52:53]
	v_cndmask_b32_e64 v75, v75, v198, s[54:55]
	v_cndmask_b32_e64 v76, v76, v198, s[56:57]
	v_cndmask_b32_e64 v77, v77, v198, s[58:59]
	v_cndmask_b32_e64 v78, v78, v198, s[60:61]
	v_cndmask_b32_e64 v79, v79, v198, s[62:63]
	v_cmp_gt_i32_e64 s[48:49], 32, v184
	v_cmp_gt_i32_e64 s[50:51], 33, v184
	v_cmp_gt_i32_e64 s[52:53], 34, v184
	v_cmp_gt_i32_e64 s[54:55], 35, v184
	v_cmp_gt_i32_e64 s[56:57], 40, v184
	v_cmp_gt_i32_e64 s[58:59], 41, v184
	v_cmp_gt_i32_e64 s[60:61], 42, v184
	v_cmp_gt_i32_e64 s[62:63], 43, v184
	v_cndmask_b32_e64 v80, v80, v198, s[48:49]
	v_cndmask_b32_e64 v81, v81, v198, s[50:51]
	v_cndmask_b32_e64 v82, v82, v198, s[52:53]
	v_cndmask_b32_e64 v83, v83, v198, s[54:55]
	v_cndmask_b32_e64 v84, v84, v198, s[56:57]
	v_cndmask_b32_e64 v85, v85, v198, s[58:59]
	v_cndmask_b32_e64 v86, v86, v198, s[60:61]
	v_cndmask_b32_e64 v87, v87, v198, s[62:63]
	v_cmp_gt_i32_e64 s[48:49], 48, v184
	v_cmp_gt_i32_e64 s[50:51], 49, v184
	v_cmp_gt_i32_e64 s[52:53], 50, v184
	v_cmp_gt_i32_e64 s[54:55], 51, v184
	v_cmp_gt_i32_e64 s[56:57], 56, v184
	v_cmp_gt_i32_e64 s[58:59], 57, v184
	v_cmp_gt_i32_e64 s[60:61], 58, v184
	v_cmp_gt_i32_e64 s[62:63], 59, v184
	v_cndmask_b32_e64 v88, v88, v198, s[48:49]
	v_cndmask_b32_e64 v89, v89, v198, s[50:51]
	v_cndmask_b32_e64 v90, v90, v198, s[52:53]
	v_cndmask_b32_e64 v91, v91, v198, s[54:55]
	v_cndmask_b32_e64 v92, v92, v198, s[56:57]
	v_cndmask_b32_e64 v93, v93, v198, s[58:59]
	v_cndmask_b32_e64 v94, v94, v198, s[60:61]
	v_cndmask_b32_e64 v95, v95, v198, s[62:63]
.Lat_nme:
	v_add_u32_e32 v184, 0xffffffc0, v184
	v_max_f32_e32 v200, v65, v65
	v_max_f32_e32 v201, v64, v64
	s_waitcnt lgkmcnt(0)
	v_mfma_f32_32x32x16_bf16 v[32:47], v[204:207], v[220:223], v[32:47]
	ds_read_b64_tr_b16 v[220:221], v165 offset:512
	ds_read_b64_tr_b16 v[222:223], v165 offset:2560
	v_max_f32_e32 v200, v201, v200
	v_max3_f32 v200, v200, v66, v67
	v_max3_f32 v200, v200, v68, v69
	v_max3_f32 v200, v200, v70, v71
	v_max3_f32 v200, v200, v72, v73
	v_max3_f32 v200, v200, v74, v75
	v_mfma_f32_32x32x16_bf16 v[32:47], v[208:211], v[224:227], v[32:47]
	ds_read_b64_tr_b16 v[224:225], v165 offset:4608
	ds_read_b64_tr_b16 v[226:227], v165 offset:6656
	v_max3_f32 v200, v200, v76, v77
	v_max3_f32 v200, v200, v78, v79
	v_max3_f32 v200, v200, v80, v81
	v_max3_f32 v200, v200, v82, v83
	v_max3_f32 v200, v200, v84, v85
	v_max3_f32 v200, v200, v86, v87
	v_mfma_f32_32x32x16_bf16 v[32:47], v[212:215], v[228:231], v[32:47]
	ds_read_b64_tr_b16 v[228:229], v165 offset:8704
	ds_read_b64_tr_b16 v[230:231], v165 offset:10752
	v_max3_f32 v200, v200, v88, v89
	v_max3_f32 v200, v200, v90, v91
	v_max3_f32 v200, v200, v92, v93
	v_max3_f32 v200, v200, v94, v95
	v_mov_b32_e32 v201, v200
	s_nop 1
	v_mfma_f32_32x32x16_bf16 v[32:47], v[216:219], v[232:235], v[32:47]
	ds_read_b64_tr_b16 v[232:233], v165 offset:12800
	ds_read_b64_tr_b16 v[234:235], v165 offset:14848
	v_permlane32_swap_b32_e32 v200, v201
	v_max_f32_e32 v201, v201, v201
	v_max_f32_e32 v200, v200, v200
	v_max_f32_e32 v200, v200, v201
	v_sub_f32_e32 v201, v200, v203
	v_mul_f32_e32 v201, 0x3db504f3, v201
	v_cmp_ge_f32_e32 vcc, 0x41000000, v201
	s_waitcnt lgkmcnt(0)
	v_mfma_f32_32x32x16_bf16 v[48:63], v[204:207], v[220:223], v[48:63]
	ds_read_b64_tr_b16 v[220:221], v165 offset:1024
	ds_read_b64_tr_b16 v[222:223], v165 offset:3072
	v_max_f32_e32 v201, v203, v203
	v_max_f32_e32 v200, v201, v200
	v_sub_f32_e32 v201, v203, v200
	v_mul_f32_e32 v201, 0x3e0293ee, v201
	v_exp_f32_e32 v201, v201
	s_cmp_eq_u64 vcc, exec
	v_mfma_f32_32x32x16_bf16 v[48:63], v[208:211], v[224:227], v[48:63]
	ds_read_b64_tr_b16 v[224:225], v165 offset:5120
	ds_read_b64_tr_b16 v[226:227], v165 offset:7168
	s_cselect_b64 s[44:45], -1, 0
	v_cndmask_b32_e64 v202, v201, 1.0, s[44:45]
	v_cndmask_b32_e64 v203, v200, v203, s[44:45]
	v_mul_f32_e32 v248, 0xbe0293ee, v203
	v_fmamk_f32 v64, v64, 0x3e0293ee, v248
	v_fmamk_f32 v65, v65, 0x3e0293ee, v248
	v_mfma_f32_32x32x16_bf16 v[48:63], v[212:215], v[228:231], v[48:63]
	ds_read_b64_tr_b16 v[228:229], v165 offset:9216
	ds_read_b64_tr_b16 v[230:231], v165 offset:11264
	v_fmamk_f32 v66, v66, 0x3e0293ee, v248
	v_fmamk_f32 v67, v67, 0x3e0293ee, v248
	v_fmamk_f32 v68, v68, 0x3e0293ee, v248
	v_fmamk_f32 v69, v69, 0x3e0293ee, v248
	v_fmamk_f32 v70, v70, 0x3e0293ee, v248
	v_fmamk_f32 v71, v71, 0x3e0293ee, v248
	v_mfma_f32_32x32x16_bf16 v[48:63], v[216:219], v[232:235], v[48:63]
	ds_read_b64_tr_b16 v[232:233], v165 offset:13312
	ds_read_b64_tr_b16 v[234:235], v165 offset:15360
	v_fmamk_f32 v72, v72, 0x3e0293ee, v248
	v_fmamk_f32 v73, v73, 0x3e0293ee, v248
	v_fmamk_f32 v74, v74, 0x3e0293ee, v248
	v_fmamk_f32 v75, v75, 0x3e0293ee, v248
	v_fmamk_f32 v76, v76, 0x3e0293ee, v248
	v_fmamk_f32 v77, v77, 0x3e0293ee, v248
	v_fmamk_f32 v78, v78, 0x3e0293ee, v248
	s_waitcnt lgkmcnt(0)
	v_mfma_f32_32x32x16_bf16 v[16:31], v[204:207], v[220:223], v[16:31]
	ds_read_b64_tr_b16 v[220:221], v165 offset:1536
	ds_read_b64_tr_b16 v[222:223], v165 offset:3584
	v_fmamk_f32 v79, v79, 0x3e0293ee, v248
	v_fmamk_f32 v80, v80, 0x3e0293ee, v248
	v_fmamk_f32 v81, v81, 0x3e0293ee, v248
	v_fmamk_f32 v82, v82, 0x3e0293ee, v248
	v_fmamk_f32 v83, v83, 0x3e0293ee, v248
	v_fmamk_f32 v84, v84, 0x3e0293ee, v248
	v_mfma_f32_32x32x16_bf16 v[16:31], v[208:211], v[224:227], v[16:31]
	ds_read_b64_tr_b16 v[224:225], v165 offset:5632
	ds_read_b64_tr_b16 v[226:227], v165 offset:7680
	v_fmamk_f32 v85, v85, 0x3e0293ee, v248
	v_fmamk_f32 v86, v86, 0x3e0293ee, v248
	v_fmamk_f32 v87, v87, 0x3e0293ee, v248
	v_fmamk_f32 v88, v88, 0x3e0293ee, v248
	v_fmamk_f32 v89, v89, 0x3e0293ee, v248
	v_fmamk_f32 v90, v90, 0x3e0293ee, v248
	v_mfma_f32_32x32x16_bf16 v[16:31], v[212:215], v[228:231], v[16:31]
	ds_read_b64_tr_b16 v[228:229], v165 offset:9728
	ds_read_b64_tr_b16 v[230:231], v165 offset:11776
	v_fmamk_f32 v91, v91, 0x3e0293ee, v248
	v_fmamk_f32 v92, v92, 0x3e0293ee, v248
	v_fmamk_f32 v93, v93, 0x3e0293ee, v248
	v_fmamk_f32 v94, v94, 0x3e0293ee, v248
	v_fmamk_f32 v95, v95, 0x3e0293ee, v248
	v_exp_f32_e32 v64, v64
	v_mfma_f32_32x32x16_bf16 v[16:31], v[216:219], v[232:235], v[16:31]
	ds_read_b64_tr_b16 v[232:233], v165 offset:13824
	ds_read_b64_tr_b16 v[234:235], v165 offset:15872
	v_exp_f32_e32 v65, v65
	v_add_f32_e32 v249, 0, v64
	v_exp_f32_e32 v66, v66
	v_add_f32_e32 v249, v65, v249
	v_exp_f32_e32 v67, v67
	v_add_f32_e32 v249, v66, v249
	v_exp_f32_e32 v68, v68
	s_waitcnt lgkmcnt(0)
	v_mfma_f32_32x32x16_bf16 v[0:15], v[204:207], v[220:223], v[0:15]
	v_add_f32_e32 v249, v67, v249
	v_exp_f32_e32 v69, v69
	v_add_f32_e32 v249, v68, v249
	v_exp_f32_e32 v70, v70
	v_add_f32_e32 v249, v69, v249
	v_exp_f32_e32 v71, v71
	v_mfma_f32_32x32x16_bf16 v[0:15], v[208:211], v[224:227], v[0:15]
	v_add_f32_e32 v249, v70, v249
	v_exp_f32_e32 v72, v72
	v_add_f32_e32 v249, v71, v249
	v_exp_f32_e32 v73, v73
	v_add_f32_e32 v249, v72, v249
	v_exp_f32_e32 v74, v74
	v_mfma_f32_32x32x16_bf16 v[0:15], v[212:215], v[228:231], v[0:15]
	v_add_f32_e32 v249, v73, v249
	v_exp_f32_e32 v75, v75
	v_add_f32_e32 v249, v74, v249
	v_exp_f32_e32 v76, v76
	v_add_f32_e32 v249, v75, v249
	v_exp_f32_e32 v77, v77
	v_mfma_f32_32x32x16_bf16 v[0:15], v[216:219], v[232:235], v[0:15]
	v_add_f32_e32 v249, v76, v249
	v_exp_f32_e32 v78, v78
	v_add_f32_e32 v249, v77, v249
	v_exp_f32_e32 v79, v79
	v_add_f32_e32 v249, v78, v249
	v_cmp_gt_f32_e32 vcc, 1.0, v202
	s_cbranch_vccz .Lat_nre
	s_nop 7
	s_nop 7
	s_and_saveexec_b64 s[4:5], s[0:1]
	ds_write_b32 v183, v202
	s_or_b64 exec, exec, s[4:5]
	s_waitcnt lgkmcnt(0)
	ds_read_b128 v[244:247], v177 offset:0
	s_waitcnt lgkmcnt(0)
	v_pk_mul_f32 v[32:33], v[32:33], v[244:245]
	v_pk_mul_f32 v[34:35], v[34:35], v[246:247]
	v_pk_mul_f32 v[48:49], v[48:49], v[244:245]
	v_pk_mul_f32 v[50:51], v[50:51], v[246:247]
	v_pk_mul_f32 v[16:17], v[16:17], v[244:245]
	v_pk_mul_f32 v[18:19], v[18:19], v[246:247]
	v_pk_mul_f32 v[0:1], v[0:1], v[244:245]
	v_pk_mul_f32 v[2:3], v[2:3], v[246:247]
	ds_read_b128 v[244:247], v177 offset:32
	s_waitcnt lgkmcnt(0)
	v_pk_mul_f32 v[36:37], v[36:37], v[244:245]
	v_pk_mul_f32 v[38:39], v[38:39], v[246:247]
	v_pk_mul_f32 v[52:53], v[52:53], v[244:245]
	v_pk_mul_f32 v[54:55], v[54:55], v[246:247]
	v_pk_mul_f32 v[20:21], v[20:21], v[244:245]
	v_pk_mul_f32 v[22:23], v[22:23], v[246:247]
	v_pk_mul_f32 v[4:5], v[4:5], v[244:245]
	v_pk_mul_f32 v[6:7], v[6:7], v[246:247]
	ds_read_b128 v[244:247], v177 offset:64
	s_waitcnt lgkmcnt(0)
	v_pk_mul_f32 v[40:41], v[40:41], v[244:245]
	v_pk_mul_f32 v[42:43], v[42:43], v[246:247]
	v_pk_mul_f32 v[56:57], v[56:57], v[244:245]
	v_pk_mul_f32 v[58:59], v[58:59], v[246:247]
	v_pk_mul_f32 v[24:25], v[24:25], v[244:245]
	v_pk_mul_f32 v[26:27], v[26:27], v[246:247]
	v_pk_mul_f32 v[8:9], v[8:9], v[244:245]
	v_pk_mul_f32 v[10:11], v[10:11], v[246:247]
	ds_read_b128 v[244:247], v177 offset:96
	s_waitcnt lgkmcnt(0)
	v_pk_mul_f32 v[44:45], v[44:45], v[244:245]
	v_pk_mul_f32 v[46:47], v[46:47], v[246:247]
	v_pk_mul_f32 v[60:61], v[60:61], v[244:245]
	v_pk_mul_f32 v[62:63], v[62:63], v[246:247]
	v_pk_mul_f32 v[28:29], v[28:29], v[244:245]
	v_pk_mul_f32 v[30:31], v[30:31], v[246:247]
	v_pk_mul_f32 v[12:13], v[12:13], v[244:245]
	v_pk_mul_f32 v[14:15], v[14:15], v[246:247]
.Lat_nre:
	ds_read_b128 v[236:239], v186 offset:49152
	ds_read_b128 v[240:243], v186 offset:57344
	v_cvt_f32_u32_e32 v204, s13
	v_mov_b32_e32 v165, v164
	v_fma_f32 v204, v172, v204, v179
	v_add_f32_e32 v208, v173, v204
	v_add_f32_e32 v212, v173, v208
	v_add_f32_e32 v216, v173, v212
	v_add_f32_e32 v205, v172, v204
	v_add_f32_e32 v209, v172, v208
	v_add_f32_e32 v213, v172, v212
	v_add_f32_e32 v217, v172, v216
	v_pk_add_f32 v[206:207], v[162:163], v[204:205] op_sel_hi:[1,0]
	v_pk_add_f32 v[210:211], v[162:163], v[208:209] op_sel_hi:[1,0]
	v_pk_add_f32 v[214:215], v[162:163], v[212:213] op_sel_hi:[1,0]
	v_pk_add_f32 v[218:219], v[162:163], v[216:217] op_sel_hi:[1,0]
	v_pk_add_f32 v[222:223], v[164:165], v[206:207]
	v_pk_add_f32 v[220:221], v[166:167], v[204:205]
	v_pk_add_f32 v[226:227], v[164:165], v[210:211]
	v_pk_add_f32 v[224:225], v[164:165], v[208:209]
	v_pk_add_f32 v[230:231], v[164:165], v[214:215]
	v_pk_add_f32 v[228:229], v[164:165], v[212:213]
	v_pk_add_f32 v[234:235], v[164:165], v[218:219]
	v_pk_add_f32 v[232:233], v[164:165], v[216:217]
	s_addk_i32 s13, 0x40
	v_exp_f32_e32 v80, v80
	s_waitcnt lgkmcnt(1)
	v_mfma_f32_32x32x16_bf16 v[204:219], v[236:239], v[104:107], v[204:219]
	ds_read_b128 v[236:239], v187 offset:49152
	v_add_f32_e32 v249, v79, v249
	v_exp_f32_e32 v81, v81
	v_add_f32_e32 v249, v80, v249
	v_exp_f32_e32 v82, v82
	s_waitcnt lgkmcnt(1)
	v_mfma_f32_32x32x16_bf16 v[220:235], v[240:243], v[104:107], v[220:235]
	ds_read_b128 v[240:243], v187 offset:57344
	v_add_f32_e32 v249, v81, v249
	v_exp_f32_e32 v83, v83
	v_add_f32_e32 v249, v82, v249
	v_exp_f32_e32 v84, v84
	s_waitcnt lgkmcnt(1)
	v_mfma_f32_32x32x16_bf16 v[204:219], v[236:239], v[108:111], v[204:219]
	ds_read_b128 v[236:239], v188 offset:49152
	v_add_f32_e32 v249, v83, v249
	v_exp_f32_e32 v85, v85
	v_add_f32_e32 v249, v84, v249
	v_exp_f32_e32 v86, v86
	s_waitcnt lgkmcnt(1)
	v_mfma_f32_32x32x16_bf16 v[220:235], v[240:243], v[108:111], v[220:235]
	ds_read_b128 v[240:243], v188 offset:57344
	v_add_f32_e32 v249, v85, v249
	v_exp_f32_e32 v87, v87
	v_add_f32_e32 v249, v86, v249
	v_exp_f32_e32 v88, v88
	s_waitcnt lgkmcnt(1)
	v_mfma_f32_32x32x16_bf16 v[204:219], v[236:239], v[112:115], v[204:219]
	ds_read_b128 v[236:239], v189 offset:49152
	v_add_f32_e32 v249, v87, v249
	v_exp_f32_e32 v89, v89
	v_add_f32_e32 v249, v88, v249
	v_exp_f32_e32 v90, v90
	s_waitcnt lgkmcnt(1)
	v_mfma_f32_32x32x16_bf16 v[220:235], v[240:243], v[112:115], v[220:235]
	ds_read_b128 v[240:243], v189 offset:57344
	v_add_f32_e32 v249, v89, v249
	v_exp_f32_e32 v91, v91
	v_add_f32_e32 v249, v90, v249
	v_exp_f32_e32 v92, v92
	s_waitcnt lgkmcnt(1)
	v_mfma_f32_32x32x16_bf16 v[204:219], v[236:239], v[116:119], v[204:219]
	ds_read_b128 v[236:239], v186 offset:49280
	v_add_f32_e32 v249, v91, v249
	v_exp_f32_e32 v93, v93
	v_add_f32_e32 v249, v92, v249
	v_exp_f32_e32 v94, v94
	s_waitcnt lgkmcnt(1)
	v_mfma_f32_32x32x16_bf16 v[220:235], v[240:243], v[116:119], v[220:235]
	ds_read_b128 v[240:243], v186 offset:57472
	v_add_f32_e32 v249, v93, v249
	v_exp_f32_e32 v95, v95
	v_add_f32_e32 v249, v94, v249
	s_nop 0
	s_waitcnt lgkmcnt(1)
	v_mfma_f32_32x32x16_bf16 v[204:219], v[236:239], v[120:123], v[204:219]
	ds_read_b128 v[236:239], v187 offset:49280
	v_add_f32_e32 v249, v95, v249
	v_mov_b32_e32 v170, v249
	s_nop 1
	v_permlane32_swap_b32_e32 v249, v170
	s_waitcnt lgkmcnt(1)
	v_mfma_f32_32x32x16_bf16 v[220:235], v[240:243], v[120:123], v[220:235]
	ds_read_b128 v[240:243], v187 offset:57472
	v_cvt_pk_bf16_f32 v64, v64, v65
	v_cvt_pk_bf16_f32 v65, v66, v67
	v_cvt_pk_bf16_f32 v66, v68, v69
	v_cvt_pk_bf16_f32 v67, v70, v71
	s_waitcnt lgkmcnt(1)
	v_mfma_f32_32x32x16_bf16 v[204:219], v[236:239], v[124:127], v[204:219]
	ds_read_b128 v[236:239], v188 offset:49280
	v_cvt_pk_bf16_f32 v68, v72, v73
	v_cvt_pk_bf16_f32 v69, v74, v75
	v_cvt_pk_bf16_f32 v70, v76, v77
	v_cvt_pk_bf16_f32 v71, v78, v79
	s_waitcnt lgkmcnt(1)
	v_mfma_f32_32x32x16_bf16 v[220:235], v[240:243], v[124:127], v[220:235]
	ds_read_b128 v[240:243], v188 offset:57472
	v_cvt_pk_bf16_f32 v72, v80, v81
	v_cvt_pk_bf16_f32 v73, v82, v83
	v_cvt_pk_bf16_f32 v74, v84, v85
	v_cvt_pk_bf16_f32 v75, v86, v87
	s_waitcnt lgkmcnt(1)
	v_mfma_f32_32x32x16_bf16 v[204:219], v[236:239], v[128:131], v[204:219]
	ds_read_b128 v[236:239], v189 offset:49280
	v_cvt_pk_bf16_f32 v76, v88, v89
	v_cvt_pk_bf16_f32 v77, v90, v91
	v_cvt_pk_bf16_f32 v78, v92, v93
	v_cvt_pk_bf16_f32 v79, v94, v95
	s_waitcnt lgkmcnt(1)
	v_mfma_f32_32x32x16_bf16 v[220:235], v[240:243], v[128:131], v[220:235]
	ds_read_b128 v[240:243], v189 offset:57472
	v_permlane32_swap_b32_e32 v64, v66
	v_permlane32_swap_b32_e32 v65, v67
	v_permlane32_swap_b32_e32 v68, v70
	v_permlane32_swap_b32_e32 v69, v71
	s_waitcnt lgkmcnt(1)
	v_mfma_f32_32x32x16_bf16 v[204:219], v[236:239], v[132:135], v[204:219]
	v_permlane32_swap_b32_e32 v72, v74
	v_permlane32_swap_b32_e32 v73, v75
	v_permlane32_swap_b32_e32 v76, v78
	v_permlane32_swap_b32_e32 v77, v79
	s_waitcnt lgkmcnt(0)
	v_mfma_f32_32x32x16_bf16 v[220:235], v[240:243], v[132:135], v[220:235]
	v_add_f32_e32 v171, v249, v170
	v_fmac_f32_e32 v171, v185, v202
	v_mov_b32_e32 v185, v171
	s_waitcnt vmcnt(0)
	v_add_u32_e32 v200, s8, v180
	v_add_u32_e32 v201, s8, v181
	ds_write_b128 v200, v[96:99]
	ds_write_b128 v201, v[100:103]
	s_and_b64 vcc, exec, s[34:35]
	s_cbranch_vccz .Lat_nwe
	ds_write_b128 v182, v[136:139] offset:32768
	ds_write_b128 v182, v[140:143] offset:40960
.Lat_nwe:
	s_mov_b32 s9, s6
	s_mov_b32 s6, s7
	s_mov_b32 s7, s8
	s_mov_b32 s8, s9
	s_waitcnt lgkmcnt(0)
	s_barrier
	s_and_b64 vcc, exec, s[34:35]
	s_cbranch_vccz .Lat_nlo
	global_load_dwordx4 v[96:99], v168, s[22:23]
	global_load_dwordx4 v[100:103], v168, s[20:21]
	global_load_dwordx4 v[136:139], v169, s[42:43]
	global_load_dwordx4 v[140:143], v169, s[26:27]
.Lat_nlo:
	v_add_u32_e32 v168, 0x4000, v168
	v_add_u32_e32 v169, 0x4000, v169
	v_add_u32_e32 v165, s6, v178
	s_add_i32 s5, s13, -1
	s_cmp_gt_i32 s5, s39
	s_cselect_b64 s[46:47], -1, 0
	ds_read_b64_tr_b16 v[80:81], v165 offset:0
	ds_read_b64_tr_b16 v[82:83], v165 offset:2048
	ds_read_b64_tr_b16 v[84:85], v165 offset:4096
	ds_read_b64_tr_b16 v[86:87], v165 offset:6144
	ds_read_b64_tr_b16 v[88:89], v165 offset:8192
	ds_read_b64_tr_b16 v[90:91], v165 offset:10240
	ds_read_b64_tr_b16 v[92:93], v165 offset:12288
	ds_read_b64_tr_b16 v[94:95], v165 offset:14336
	s_and_b64 vcc, exec, s[46:47]
	s_cbranch_vccz .Lat_nmo
	v_cmp_gt_i32_e64 s[48:49], 0, v184
	v_cmp_gt_i32_e64 s[50:51], 1, v184
	v_cmp_gt_i32_e64 s[52:53], 2, v184
	v_cmp_gt_i32_e64 s[54:55], 3, v184
	v_cmp_gt_i32_e64 s[56:57], 8, v184
	v_cmp_gt_i32_e64 s[58:59], 9, v184
	v_cmp_gt_i32_e64 s[60:61], 10, v184
	v_cmp_gt_i32_e64 s[62:63], 11, v184
	v_cndmask_b32_e64 v204, v204, v198, s[48:49]
	v_cndmask_b32_e64 v205, v205, v198, s[50:51]
	v_cndmask_b32_e64 v206, v206, v198, s[52:53]
	v_cndmask_b32_e64 v207, v207, v198, s[54:55]
	v_cndmask_b32_e64 v208, v208, v198, s[56:57]
	v_cndmask_b32_e64 v209, v209, v198, s[58:59]
	v_cndmask_b32_e64 v210, v210, v198, s[60:61]
	v_cndmask_b32_e64 v211, v211, v198, s[62:63]
	v_cmp_gt_i32_e64 s[48:49], 16, v184
	v_cmp_gt_i32_e64 s[50:51], 17, v184
	v_cmp_gt_i32_e64 s[52:53], 18, v184
	v_cmp_gt_i32_e64 s[54:55], 19, v184
	v_cmp_gt_i32_e64 s[56:57], 24, v184
	v_cmp_gt_i32_e64 s[58:59], 25, v184
	v_cmp_gt_i32_e64 s[60:61], 26, v184
	v_cmp_gt_i32_e64 s[62:63], 27, v184
	v_cndmask_b32_e64 v212, v212, v198, s[48:49]
	v_cndmask_b32_e64 v213, v213, v198, s[50:51]
	v_cndmask_b32_e64 v214, v214, v198, s[52:53]
	v_cndmask_b32_e64 v215, v215, v198, s[54:55]
	v_cndmask_b32_e64 v216, v216, v198, s[56:57]
	v_cndmask_b32_e64 v217, v217, v198, s[58:59]
	v_cndmask_b32_e64 v218, v218, v198, s[60:61]
	v_cndmask_b32_e64 v219, v219, v198, s[62:63]
	v_cmp_gt_i32_e64 s[48:49], 32, v184
	v_cmp_gt_i32_e64 s[50:51], 33, v184
	v_cmp_gt_i32_e64 s[52:53], 34, v184
	v_cmp_gt_i32_e64 s[54:55], 35, v184
	v_cmp_gt_i32_e64 s[56:57], 40, v184
	v_cmp_gt_i32_e64 s[58:59], 41, v184
	v_cmp_gt_i32_e64 s[60:61], 42, v184
	v_cmp_gt_i32_e64 s[62:63], 43, v184
	v_cndmask_b32_e64 v220, v220, v198, s[48:49]
	v_cndmask_b32_e64 v221, v221, v198, s[50:51]
	v_cndmask_b32_e64 v222, v222, v198, s[52:53]
	v_cndmask_b32_e64 v223, v223, v198, s[54:55]
	v_cndmask_b32_e64 v224, v224, v198, s[56:57]
	v_cndmask_b32_e64 v225, v225, v198, s[58:59]
	v_cndmask_b32_e64 v226, v226, v198, s[60:61]
	v_cndmask_b32_e64 v227, v227, v198, s[62:63]
	v_cmp_gt_i32_e64 s[48:49], 48, v184
	v_cmp_gt_i32_e64 s[50:51], 49, v184
	v_cmp_gt_i32_e64 s[52:53], 50, v184
	v_cmp_gt_i32_e64 s[54:55], 51, v184
	v_cmp_gt_i32_e64 s[56:57], 56, v184
	v_cmp_gt_i32_e64 s[58:59], 57, v184
	v_cmp_gt_i32_e64 s[60:61], 58, v184
	v_cmp_gt_i32_e64 s[62:63], 59, v184
	v_cndmask_b32_e64 v228, v228, v198, s[48:49]
	v_cndmask_b32_e64 v229, v229, v198, s[50:51]
	v_cndmask_b32_e64 v230, v230, v198, s[52:53]
	v_cndmask_b32_e64 v231, v231, v198, s[54:55]
	v_cndmask_b32_e64 v232, v232, v198, s[56:57]
	v_cndmask_b32_e64 v233, v233, v198, s[58:59]
	v_cndmask_b32_e64 v234, v234, v198, s[60:61]
	v_cndmask_b32_e64 v235, v235, v198, s[62:63]
.Lat_nmo:
	v_add_u32_e32 v184, 0xffffffc0, v184
	v_max_f32_e32 v200, v205, v205
	v_max_f32_e32 v201, v204, v204
	s_waitcnt lgkmcnt(0)
	v_mfma_f32_32x32x16_bf16 v[32:47], v[64:67], v[80:83], v[32:47]
	ds_read_b64_tr_b16 v[80:81], v165 offset:512
	ds_read_b64_tr_b16 v[82:83], v165 offset:2560
	v_max_f32_e32 v200, v201, v200
	v_max3_f32 v200, v200, v206, v207
	v_max3_f32 v200, v200, v208, v209
	v_max3_f32 v200, v200, v210, v211
	v_max3_f32 v200, v200, v212, v213
	v_max3_f32 v200, v200, v214, v215
	v_mfma_f32_32x32x16_bf16 v[32:47], v[68:71], v[84:87], v[32:47]
	ds_read_b64_tr_b16 v[84:85], v165 offset:4608
	ds_read_b64_tr_b16 v[86:87], v165 offset:6656
	v_max3_f32 v200, v200, v216, v217
	v_max3_f32 v200, v200, v218, v219
	v_max3_f32 v200, v200, v220, v221
	v_max3_f32 v200, v200, v222, v223
	v_max3_f32 v200, v200, v224, v225
	v_max3_f32 v200, v200, v226, v227
	v_mfma_f32_32x32x16_bf16 v[32:47], v[72:75], v[88:91], v[32:47]
	ds_read_b64_tr_b16 v[88:89], v165 offset:8704
	ds_read_b64_tr_b16 v[90:91], v165 offset:10752
	v_max3_f32 v200, v200, v228, v229
	v_max3_f32 v200, v200, v230, v231
	v_max3_f32 v200, v200, v232, v233
	v_max3_f32 v200, v200, v234, v235
	v_mov_b32_e32 v201, v200
	s_nop 1
	v_mfma_f32_32x32x16_bf16 v[32:47], v[76:79], v[92:95], v[32:47]
	ds_read_b64_tr_b16 v[92:93], v165 offset:12800
	ds_read_b64_tr_b16 v[94:95], v165 offset:14848
	v_permlane32_swap_b32_e32 v200, v201
	v_max_f32_e32 v201, v201, v201
	v_max_f32_e32 v200, v200, v200
	v_max_f32_e32 v200, v200, v201
	v_sub_f32_e32 v201, v200, v203
	v_mul_f32_e32 v201, 0x3db504f3, v201
	v_cmp_ge_f32_e32 vcc, 0x41000000, v201
	s_waitcnt lgkmcnt(0)
	v_mfma_f32_32x32x16_bf16 v[48:63], v[64:67], v[80:83], v[48:63]
	ds_read_b64_tr_b16 v[80:81], v165 offset:1024
	ds_read_b64_tr_b16 v[82:83], v165 offset:3072
	v_max_f32_e32 v201, v203, v203
	v_max_f32_e32 v200, v201, v200
	v_sub_f32_e32 v201, v203, v200
	v_mul_f32_e32 v201, 0x3e0293ee, v201
	v_exp_f32_e32 v201, v201
	s_cmp_eq_u64 vcc, exec
	v_mfma_f32_32x32x16_bf16 v[48:63], v[68:71], v[84:87], v[48:63]
	ds_read_b64_tr_b16 v[84:85], v165 offset:5120
	ds_read_b64_tr_b16 v[86:87], v165 offset:7168
	s_cselect_b64 s[44:45], -1, 0
	v_cndmask_b32_e64 v202, v201, 1.0, s[44:45]
	v_cndmask_b32_e64 v203, v200, v203, s[44:45]
	v_mul_f32_e32 v248, 0xbe0293ee, v203
	v_fmamk_f32 v204, v204, 0x3e0293ee, v248
	v_fmamk_f32 v205, v205, 0x3e0293ee, v248
	v_mfma_f32_32x32x16_bf16 v[48:63], v[72:75], v[88:91], v[48:63]
	ds_read_b64_tr_b16 v[88:89], v165 offset:9216
	ds_read_b64_tr_b16 v[90:91], v165 offset:11264
	v_fmamk_f32 v206, v206, 0x3e0293ee, v248
	v_fmamk_f32 v207, v207, 0x3e0293ee, v248
	v_fmamk_f32 v208, v208, 0x3e0293ee, v248
	v_fmamk_f32 v209, v209, 0x3e0293ee, v248
	v_fmamk_f32 v210, v210, 0x3e0293ee, v248
	v_fmamk_f32 v211, v211, 0x3e0293ee, v248
	v_mfma_f32_32x32x16_bf16 v[48:63], v[76:79], v[92:95], v[48:63]
	ds_read_b64_tr_b16 v[92:93], v165 offset:13312
	ds_read_b64_tr_b16 v[94:95], v165 offset:15360
	v_fmamk_f32 v212, v212, 0x3e0293ee, v248
	v_fmamk_f32 v213, v213, 0x3e0293ee, v248
	v_fmamk_f32 v214, v214, 0x3e0293ee, v248
	v_fmamk_f32 v215, v215, 0x3e0293ee, v248
	v_fmamk_f32 v216, v216, 0x3e0293ee, v248
	v_fmamk_f32 v217, v217, 0x3e0293ee, v248
	v_fmamk_f32 v218, v218, 0x3e0293ee, v248
	s_waitcnt lgkmcnt(0)
	v_mfma_f32_32x32x16_bf16 v[16:31], v[64:67], v[80:83], v[16:31]
	ds_read_b64_tr_b16 v[80:81], v165 offset:1536
	ds_read_b64_tr_b16 v[82:83], v165 offset:3584
	v_fmamk_f32 v219, v219, 0x3e0293ee, v248
	v_fmamk_f32 v220, v220, 0x3e0293ee, v248
	v_fmamk_f32 v221, v221, 0x3e0293ee, v248
	v_fmamk_f32 v222, v222, 0x3e0293ee, v248
	v_fmamk_f32 v223, v223, 0x3e0293ee, v248
	v_fmamk_f32 v224, v224, 0x3e0293ee, v248
	v_mfma_f32_32x32x16_bf16 v[16:31], v[68:71], v[84:87], v[16:31]
	ds_read_b64_tr_b16 v[84:85], v165 offset:5632
	ds_read_b64_tr_b16 v[86:87], v165 offset:7680
	v_fmamk_f32 v225, v225, 0x3e0293ee, v248
	v_fmamk_f32 v226, v226, 0x3e0293ee, v248
	v_fmamk_f32 v227, v227, 0x3e0293ee, v248
	v_fmamk_f32 v228, v228, 0x3e0293ee, v248
	v_fmamk_f32 v229, v229, 0x3e0293ee, v248
	v_fmamk_f32 v230, v230, 0x3e0293ee, v248
	v_mfma_f32_32x32x16_bf16 v[16:31], v[72:75], v[88:91], v[16:31]
	ds_read_b64_tr_b16 v[88:89], v165 offset:9728
	ds_read_b64_tr_b16 v[90:91], v165 offset:11776
	v_fmamk_f32 v231, v231, 0x3e0293ee, v248
	v_fmamk_f32 v232, v232, 0x3e0293ee, v248
	v_fmamk_f32 v233, v233, 0x3e0293ee, v248
	v_fmamk_f32 v234, v234, 0x3e0293ee, v248
	v_fmamk_f32 v235, v235, 0x3e0293ee, v248
	v_exp_f32_e32 v204, v204
	v_mfma_f32_32x32x16_bf16 v[16:31], v[76:79], v[92:95], v[16:31]
	ds_read_b64_tr_b16 v[92:93], v165 offset:13824
	ds_read_b64_tr_b16 v[94:95], v165 offset:15872
	v_exp_f32_e32 v205, v205
	v_add_f32_e32 v249, 0, v204
	v_exp_f32_e32 v206, v206
	v_add_f32_e32 v249, v205, v249
	v_exp_f32_e32 v207, v207
	v_add_f32_e32 v249, v206, v249
	v_exp_f32_e32 v208, v208
	s_waitcnt lgkmcnt(0)
	v_mfma_f32_32x32x16_bf16 v[0:15], v[64:67], v[80:83], v[0:15]
	v_add_f32_e32 v249, v207, v249
	v_exp_f32_e32 v209, v209
	v_add_f32_e32 v249, v208, v249
	v_exp_f32_e32 v210, v210
	v_add_f32_e32 v249, v209, v249
	v_exp_f32_e32 v211, v211
	v_mfma_f32_32x32x16_bf16 v[0:15], v[68:71], v[84:87], v[0:15]
	v_add_f32_e32 v249, v210, v249
	v_exp_f32_e32 v212, v212
	v_add_f32_e32 v249, v211, v249
	v_exp_f32_e32 v213, v213
	v_add_f32_e32 v249, v212, v249
	v_exp_f32_e32 v214, v214
	v_mfma_f32_32x32x16_bf16 v[0:15], v[72:75], v[88:91], v[0:15]
	v_add_f32_e32 v249, v213, v249
	v_exp_f32_e32 v215, v215
	v_add_f32_e32 v249, v214, v249
	v_exp_f32_e32 v216, v216
	v_add_f32_e32 v249, v215, v249
	v_exp_f32_e32 v217, v217
	v_mfma_f32_32x32x16_bf16 v[0:15], v[76:79], v[92:95], v[0:15]
	v_add_f32_e32 v249, v216, v249
	v_exp_f32_e32 v218, v218
	v_add_f32_e32 v249, v217, v249
	v_exp_f32_e32 v219, v219
	v_add_f32_e32 v249, v218, v249
	v_cmp_gt_f32_e32 vcc, 1.0, v202
	s_cbranch_vccz .Lat_nro
	s_nop 7
	s_nop 7
	s_and_saveexec_b64 s[4:5], s[0:1]
	ds_write_b32 v183, v202
	s_or_b64 exec, exec, s[4:5]
	s_waitcnt lgkmcnt(0)
	ds_read_b128 v[244:247], v177 offset:0
	s_waitcnt lgkmcnt(0)
	v_pk_mul_f32 v[32:33], v[32:33], v[244:245]
	v_pk_mul_f32 v[34:35], v[34:35], v[246:247]
	v_pk_mul_f32 v[48:49], v[48:49], v[244:245]
	v_pk_mul_f32 v[50:51], v[50:51], v[246:247]
	v_pk_mul_f32 v[16:17], v[16:17], v[244:245]
	v_pk_mul_f32 v[18:19], v[18:19], v[246:247]
	v_pk_mul_f32 v[0:1], v[0:1], v[244:245]
	v_pk_mul_f32 v[2:3], v[2:3], v[246:247]
	ds_read_b128 v[244:247], v177 offset:32
	s_waitcnt lgkmcnt(0)
	v_pk_mul_f32 v[36:37], v[36:37], v[244:245]
	v_pk_mul_f32 v[38:39], v[38:39], v[246:247]
	v_pk_mul_f32 v[52:53], v[52:53], v[244:245]
	v_pk_mul_f32 v[54:55], v[54:55], v[246:247]
	v_pk_mul_f32 v[20:21], v[20:21], v[244:245]
	v_pk_mul_f32 v[22:23], v[22:23], v[246:247]
	v_pk_mul_f32 v[4:5], v[4:5], v[244:245]
	v_pk_mul_f32 v[6:7], v[6:7], v[246:247]
	ds_read_b128 v[244:247], v177 offset:64
	s_waitcnt lgkmcnt(0)
	v_pk_mul_f32 v[40:41], v[40:41], v[244:245]
	v_pk_mul_f32 v[42:43], v[42:43], v[246:247]
	v_pk_mul_f32 v[56:57], v[56:57], v[244:245]
	v_pk_mul_f32 v[58:59], v[58:59], v[246:247]
	v_pk_mul_f32 v[24:25], v[24:25], v[244:245]
	v_pk_mul_f32 v[26:27], v[26:27], v[246:247]
	v_pk_mul_f32 v[8:9], v[8:9], v[244:245]
	v_pk_mul_f32 v[10:11], v[10:11], v[246:247]
	ds_read_b128 v[244:247], v177 offset:96
	s_waitcnt lgkmcnt(0)
	v_pk_mul_f32 v[44:45], v[44:45], v[244:245]
	v_pk_mul_f32 v[46:47], v[46:47], v[246:247]
	v_pk_mul_f32 v[60:61], v[60:61], v[244:245]
	v_pk_mul_f32 v[62:63], v[62:63], v[246:247]
	v_pk_mul_f32 v[28:29], v[28:29], v[244:245]
	v_pk_mul_f32 v[30:31], v[30:31], v[246:247]
	v_pk_mul_f32 v[12:13], v[12:13], v[244:245]
	v_pk_mul_f32 v[14:15], v[14:15], v[246:247]
.Lat_nro:
	ds_read_b128 v[236:239], v186 offset:32768
	ds_read_b128 v[240:243], v186 offset:40960
	v_cvt_f32_u32_e32 v64, s13
	v_mov_b32_e32 v165, v164
	v_fma_f32 v64, v172, v64, v179
	v_add_f32_e32 v68, v173, v64
	v_add_f32_e32 v72, v173, v68
	v_add_f32_e32 v76, v173, v72
	v_add_f32_e32 v65, v172, v64
	v_add_f32_e32 v69, v172, v68
	v_add_f32_e32 v73, v172, v72
	v_add_f32_e32 v77, v172, v76
	v_pk_add_f32 v[66:67], v[162:163], v[64:65] op_sel_hi:[1,0]
	v_pk_add_f32 v[70:71], v[162:163], v[68:69] op_sel_hi:[1,0]
	v_pk_add_f32 v[74:75], v[162:163], v[72:73] op_sel_hi:[1,0]
	v_pk_add_f32 v[78:79], v[162:163], v[76:77] op_sel_hi:[1,0]
	v_pk_add_f32 v[82:83], v[164:165], v[66:67]
	v_pk_add_f32 v[80:81], v[166:167], v[64:65]
	v_pk_add_f32 v[86:87], v[164:165], v[70:71]
	v_pk_add_f32 v[84:85], v[164:165], v[68:69]
	v_pk_add_f32 v[90:91], v[164:165], v[74:75]
	v_pk_add_f32 v[88:89], v[164:165], v[72:73]
	v_pk_add_f32 v[94:95], v[164:165], v[78:79]
	v_pk_add_f32 v[92:93], v[164:165], v[76:77]
	s_addk_i32 s13, 0x40
	v_exp_f32_e32 v220, v220
	s_waitcnt lgkmcnt(1)
	v_mfma_f32_32x32x16_bf16 v[64:79], v[236:239], v[104:107], v[64:79]
	ds_read_b128 v[236:239], v187 offset:32768
	v_add_f32_e32 v249, v219, v249
	v_exp_f32_e32 v221, v221
	v_add_f32_e32 v249, v220, v249
	v_exp_f32_e32 v222, v222
	s_waitcnt lgkmcnt(1)
	v_mfma_f32_32x32x16_bf16 v[80:95], v[240:243], v[104:107], v[80:95]
	ds_read_b128 v[240:243], v187 offset:40960
	v_add_f32_e32 v249, v221, v249
	v_exp_f32_e32 v223, v223
	v_add_f32_e32 v249, v222, v249
	v_exp_f32_e32 v224, v224
	s_waitcnt lgkmcnt(1)
	v_mfma_f32_32x32x16_bf16 v[64:79], v[236:239], v[108:111], v[64:79]
	ds_read_b128 v[236:239], v188 offset:32768
	v_add_f32_e32 v249, v223, v249
	v_exp_f32_e32 v225, v225
	v_add_f32_e32 v249, v224, v249
	v_exp_f32_e32 v226, v226
	s_waitcnt lgkmcnt(1)
	v_mfma_f32_32x32x16_bf16 v[80:95], v[240:243], v[108:111], v[80:95]
	ds_read_b128 v[240:243], v188 offset:40960
	v_add_f32_e32 v249, v225, v249
	v_exp_f32_e32 v227, v227
	v_add_f32_e32 v249, v226, v249
	v_exp_f32_e32 v228, v228
	s_waitcnt lgkmcnt(1)
	v_mfma_f32_32x32x16_bf16 v[64:79], v[236:239], v[112:115], v[64:79]
	ds_read_b128 v[236:239], v189 offset:32768
	v_add_f32_e32 v249, v227, v249
	v_exp_f32_e32 v229, v229
	v_add_f32_e32 v249, v228, v249
	v_exp_f32_e32 v230, v230
	s_waitcnt lgkmcnt(1)
	v_mfma_f32_32x32x16_bf16 v[80:95], v[240:243], v[112:115], v[80:95]
	ds_read_b128 v[240:243], v189 offset:40960
	v_add_f32_e32 v249, v229, v249
	v_exp_f32_e32 v231, v231
	v_add_f32_e32 v249, v230, v249
	v_exp_f32_e32 v232, v232
	s_waitcnt lgkmcnt(1)
	v_mfma_f32_32x32x16_bf16 v[64:79], v[236:239], v[116:119], v[64:79]
	ds_read_b128 v[236:239], v186 offset:32896
	v_add_f32_e32 v249, v231, v249
	v_exp_f32_e32 v233, v233
	v_add_f32_e32 v249, v232, v249
	v_exp_f32_e32 v234, v234
	s_waitcnt lgkmcnt(1)
	v_mfma_f32_32x32x16_bf16 v[80:95], v[240:243], v[116:119], v[80:95]
	ds_read_b128 v[240:243], v186 offset:41088
	v_add_f32_e32 v249, v233, v249
	v_exp_f32_e32 v235, v235
	v_add_f32_e32 v249, v234, v249
	s_nop 0
	s_waitcnt lgkmcnt(1)
	v_mfma_f32_32x32x16_bf16 v[64:79], v[236:239], v[120:123], v[64:79]
	ds_read_b128 v[236:239], v187 offset:32896
	v_add_f32_e32 v249, v235, v249
	v_mov_b32_e32 v170, v249
	s_nop 1
	v_permlane32_swap_b32_e32 v249, v170
	s_waitcnt lgkmcnt(1)
	v_mfma_f32_32x32x16_bf16 v[80:95], v[240:243], v[120:123], v[80:95]
	ds_read_b128 v[240:243], v187 offset:41088
	v_cvt_pk_bf16_f32 v204, v204, v205
	v_cvt_pk_bf16_f32 v205, v206, v207
	v_cvt_pk_bf16_f32 v206, v208, v209
	v_cvt_pk_bf16_f32 v207, v210, v211
	s_waitcnt lgkmcnt(1)
	v_mfma_f32_32x32x16_bf16 v[64:79], v[236:239], v[124:127], v[64:79]
	ds_read_b128 v[236:239], v188 offset:32896
	v_cvt_pk_bf16_f32 v208, v212, v213
	v_cvt_pk_bf16_f32 v209, v214, v215
	v_cvt_pk_bf16_f32 v210, v216, v217
	v_cvt_pk_bf16_f32 v211, v218, v219
	s_waitcnt lgkmcnt(1)
	v_mfma_f32_32x32x16_bf16 v[80:95], v[240:243], v[124:127], v[80:95]
	ds_read_b128 v[240:243], v188 offset:41088
	v_cvt_pk_bf16_f32 v212, v220, v221
	v_cvt_pk_bf16_f32 v213, v222, v223
	v_cvt_pk_bf16_f32 v214, v224, v225
	v_cvt_pk_bf16_f32 v215, v226, v227
	s_waitcnt lgkmcnt(1)
	v_mfma_f32_32x32x16_bf16 v[64:79], v[236:239], v[128:131], v[64:79]
	ds_read_b128 v[236:239], v189 offset:32896
	v_cvt_pk_bf16_f32 v216, v228, v229
	v_cvt_pk_bf16_f32 v217, v230, v231
	v_cvt_pk_bf16_f32 v218, v232, v233
	v_cvt_pk_bf16_f32 v219, v234, v235
	s_waitcnt lgkmcnt(1)
	v_mfma_f32_32x32x16_bf16 v[80:95], v[240:243], v[128:131], v[80:95]
	ds_read_b128 v[240:243], v189 offset:41088
	v_permlane32_swap_b32_e32 v204, v206
	v_permlane32_swap_b32_e32 v205, v207
	v_permlane32_swap_b32_e32 v208, v210
	v_permlane32_swap_b32_e32 v209, v211
	s_waitcnt lgkmcnt(1)
	v_mfma_f32_32x32x16_bf16 v[64:79], v[236:239], v[132:135], v[64:79]
	v_permlane32_swap_b32_e32 v212, v214
	v_permlane32_swap_b32_e32 v213, v215
	v_permlane32_swap_b32_e32 v216, v218
	v_permlane32_swap_b32_e32 v217, v219
	s_waitcnt lgkmcnt(0)
	v_mfma_f32_32x32x16_bf16 v[80:95], v[240:243], v[132:135], v[80:95]
	v_add_f32_e32 v171, v249, v170
	v_fmac_f32_e32 v171, v185, v202
	v_mov_b32_e32 v185, v171
	s_waitcnt vmcnt(0)
	s_and_b64 vcc, exec, s[34:35]
	s_cbranch_vccz .Lat_nwo
	v_add_u32_e32 v200, s8, v180
	v_add_u32_e32 v201, s8, v181
	ds_write_b128 v200, v[96:99]
	ds_write_b128 v201, v[100:103]
	ds_write_b128 v182, v[136:139] offset:49152
	ds_write_b128 v182, v[140:143] offset:57344
.Lat_nwo:
	s_mov_b32 s9, s6
	s_mov_b32 s6, s7
	s_mov_b32 s7, s8
	s_mov_b32 s8, s9
	s_waitcnt lgkmcnt(0)
	s_barrier
	s_add_i32 s12, s12, 2
	s_cmp_lt_u32 s12, s18
	s_cbranch_scc1 .Lat_loop
	v_add_u32_e32 v165, s6, v178
	ds_read_b64_tr_b16 v[220:221], v165 offset:0
	ds_read_b64_tr_b16 v[222:223], v165 offset:2048
	ds_read_b64_tr_b16 v[224:225], v165 offset:4096
	ds_read_b64_tr_b16 v[226:227], v165 offset:6144
	ds_read_b64_tr_b16 v[228:229], v165 offset:8192
	ds_read_b64_tr_b16 v[230:231], v165 offset:10240
	ds_read_b64_tr_b16 v[232:233], v165 offset:12288
	ds_read_b64_tr_b16 v[234:235], v165 offset:14336
	s_waitcnt lgkmcnt(0)
	v_mfma_f32_32x32x16_bf16 v[32:47], v[204:207], v[220:223], v[32:47]
	ds_read_b64_tr_b16 v[220:221], v165 offset:512
	ds_read_b64_tr_b16 v[222:223], v165 offset:2560
	v_mfma_f32_32x32x16_bf16 v[32:47], v[208:211], v[224:227], v[32:47]
	ds_read_b64_tr_b16 v[224:225], v165 offset:4608
	ds_read_b64_tr_b16 v[226:227], v165 offset:6656
	v_mfma_f32_32x32x16_bf16 v[32:47], v[212:215], v[228:231], v[32:47]
	ds_read_b64_tr_b16 v[228:229], v165 offset:8704
	ds_read_b64_tr_b16 v[230:231], v165 offset:10752
	v_mfma_f32_32x32x16_bf16 v[32:47], v[216:219], v[232:235], v[32:47]
	ds_read_b64_tr_b16 v[232:233], v165 offset:12800
	ds_read_b64_tr_b16 v[234:235], v165 offset:14848
	s_waitcnt lgkmcnt(0)
	v_mfma_f32_32x32x16_bf16 v[48:63], v[204:207], v[220:223], v[48:63]
	ds_read_b64_tr_b16 v[220:221], v165 offset:1024
	ds_read_b64_tr_b16 v[222:223], v165 offset:3072
	v_mfma_f32_32x32x16_bf16 v[48:63], v[208:211], v[224:227], v[48:63]
	ds_read_b64_tr_b16 v[224:225], v165 offset:5120
	ds_read_b64_tr_b16 v[226:227], v165 offset:7168
	v_mfma_f32_32x32x16_bf16 v[48:63], v[212:215], v[228:231], v[48:63]
	ds_read_b64_tr_b16 v[228:229], v165 offset:9216
	ds_read_b64_tr_b16 v[230:231], v165 offset:11264
	v_mfma_f32_32x32x16_bf16 v[48:63], v[216:219], v[232:235], v[48:63]
	ds_read_b64_tr_b16 v[232:233], v165 offset:13312
	ds_read_b64_tr_b16 v[234:235], v165 offset:15360
	s_waitcnt lgkmcnt(0)
	v_mfma_f32_32x32x16_bf16 v[16:31], v[204:207], v[220:223], v[16:31]
	ds_read_b64_tr_b16 v[220:221], v165 offset:1536
	ds_read_b64_tr_b16 v[222:223], v165 offset:3584
	v_mfma_f32_32x32x16_bf16 v[16:31], v[208:211], v[224:227], v[16:31]
	ds_read_b64_tr_b16 v[224:225], v165 offset:5632
	ds_read_b64_tr_b16 v[226:227], v165 offset:7680
	v_mfma_f32_32x32x16_bf16 v[16:31], v[212:215], v[228:231], v[16:31]
	ds_read_b64_tr_b16 v[228:229], v165 offset:9728
	ds_read_b64_tr_b16 v[230:231], v165 offset:11776
	v_mfma_f32_32x32x16_bf16 v[16:31], v[216:219], v[232:235], v[16:31]
	ds_read_b64_tr_b16 v[232:233], v165 offset:13824
	ds_read_b64_tr_b16 v[234:235], v165 offset:15872
	s_waitcnt lgkmcnt(0)
	v_mfma_f32_32x32x16_bf16 v[0:15], v[204:207], v[220:223], v[0:15]
	v_mfma_f32_32x32x16_bf16 v[0:15], v[208:211], v[224:227], v[0:15]
	v_mfma_f32_32x32x16_bf16 v[0:15], v[212:215], v[228:231], v[0:15]
	v_mfma_f32_32x32x16_bf16 v[0:15], v[216:219], v[232:235], v[0:15]
	s_nop 7
	s_nop 7
